# P5: per-segment lane-parallel scaling pre-pass, next-step LDS operand prefetch, staging global-load waits moved behind the 4-step loop
# baseline (speedup 1.0000x reference)
; #define SCAN_LOAD(seg) do { _Pragma("unroll") for (int s = 0; s < SB; ++s) { const unsigned st_ = (unsigned)((seg) * SB + s); const unsigned ix = i0 + st_ * DB, fx = f0 + st_ * 3072u; \
;             rg[s][0] = DEC[ix]; rg[s][1] = bf2f(FEAT[fx]); rg[s][2] = bf2f(FEAT[fx + 1024]); rg[s][3] = bf2f(FEAT[fx + 2048]); rg[s][4] = bf2f(AS[ix]); } } while (0)
;     ...
;             if (MODE != 2 && seg + 1 < CL / SB) SCAN_LOAD(seg + 1);
.LBB0_1063:
	s_add_i32 s44, s43, 1
	s_cmp_lg_u32 s43, 63
	s_cselect_b64 s[66:67], -1, 0
	s_cmp_eq_u32 s43, 63
	v_lshl_add_u32 v164, s44, 12, v136
	s_cbranch_scc1 .LBB0_1065
	s_mul_i32 s46, s44, 0x3000
	s_lshl_b32 s45, s44, 2
	v_add_u32_e32 v130, s46, v138
	v_lshl_add_u64 v[148:149], v[130:131], 1, s[14:15]
	v_add_u32_e32 v152, 0x400, v130
	v_add_u32_e32 v130, 0x800, v130
	s_or_b32 s46, s45, 1
	v_lshl_add_u64 v[160:161], v[130:131], 1, s[14:15]
	v_add_u32_e32 v130, s46, v188
	s_mulk_i32 s46, 0xc00
	v_mov_b32_e32 v165, v131
	v_add_u32_e32 v166, s46, v138
	v_lshl_add_u64 v[142:143], v[164:165], 2, s[8:9]
	v_mov_b32_e32 v153, v131
	v_lshl_add_u32 v130, v130, 10, v134
	v_mov_b32_e32 v167, v131
	v_add_u32_e32 v172, 0x400, v166
	v_mov_b32_e32 v173, v131
	v_lshl_add_u64 v[152:153], v[152:153], 1, s[14:15]
	v_lshl_add_u64 v[162:163], v[164:165], 1, s[16:17]
	v_lshl_add_u64 v[168:169], v[130:131], 2, s[8:9]
	v_lshl_add_u64 v[170:171], v[166:167], 1, s[14:15]
	v_lshl_add_u64 v[172:173], v[172:173], 1, s[14:15]
	global_load_dword v189, v[142:143], off
	global_load_ushort v133, v[152:153], off
	global_load_ushort v135, v[162:163], off
	global_load_dword v139, v[168:169], off
	global_load_ushort v137, v[172:173], off
	global_load_ushort v150, v[170:171], off
	global_load_ushort v154, v[160:161], off
	global_load_ushort v248, v[148:149], off
	v_lshl_add_u64 v[148:149], v[130:131], 1, s[16:17]
	v_add_u32_e32 v130, s45, v188
	v_lshl_add_u32 v146, v130, 10, v134
	v_add_u32_e32 v142, 0x800, v166
	v_mov_b32_e32 v143, v131
	v_add_u32_e32 v130, 0x800, v146
	v_add_u32_e32 v152, 0xc00, v166
	v_mov_b32_e32 v153, v131
	v_add_u32_e32 v168, 0x1400, v166
	v_mov_b32_e32 v169, v131
	v_lshl_add_u64 v[142:143], v[142:143], 1, s[14:15]
	v_lshl_add_u64 v[160:161], v[130:131], 2, s[8:9]
	v_lshl_add_u64 v[152:153], v[152:153], 1, s[14:15]
	v_add_u32_e32 v162, 0x1000, v166
	v_mov_b32_e32 v163, v131
	v_lshl_add_u64 v[168:169], v[168:169], 1, s[14:15]
	v_lshl_add_u64 v[170:171], v[130:131], 1, s[16:17]
	v_add_u32_e32 v130, 0xc00, v146
	v_lshl_add_u64 v[162:163], v[162:163], 1, s[14:15]
	v_lshl_add_u64 v[172:173], v[130:131], 2, s[8:9]
	global_load_ushort v249, v[142:143], off
	global_load_ushort v250, v[148:149], off
	global_load_ushort v251, v[162:163], off
	s_nop 0
	global_load_ushort v252, v[168:169], off
	s_nop 0
	global_load_ushort v253, v[170:171], off
	global_load_dword v190, v[172:173], off
	s_nop 0
	global_load_ushort v220, v[152:153], off
	v_add_u32_e32 v152, 0x2000, v166
	v_mov_b32_e32 v153, v131
	v_add_u32_e32 v142, 0x1800, v166
	v_mov_b32_e32 v143, v131
	v_add_u32_e32 v148, 0x1c00, v166
	v_mov_b32_e32 v149, v131
	v_lshl_add_u64 v[152:153], v[152:153], 1, s[14:15]
	v_lshl_add_u64 v[162:163], v[130:131], 1, s[16:17]
	v_lshl_add_u64 v[148:149], v[148:149], 1, s[14:15]
	global_load_ushort v221, v[152:153], off
	s_nop 0
	global_load_ushort v162, v[162:163], off
	s_nop 0
	global_load_ushort v163, v[148:149], off
	v_lshl_add_u64 v[142:143], v[142:143], 1, s[14:15]
	global_load_ushort v222, v[142:143], off
	global_load_dword v191, v[160:161], off

;     ...
;                 const LAS float* sv = buf + ((bi * SB + s) * NV) * 64;
;                 const LAS f32x4* L4 = (const LAS f32x4*)sv;
;                 f32x2 qloa = {0.f, 0.f}, qhia = qloa, qlob = qloa, qhib = qloa, plo = qloa, phi = qloa, yloa = qloa, yhia = qloa, ylob = qloa, yhib = qloa, saq2 = qloa, sap2 = qloa;
;                 const float vv = sv[4 * 64 + lane]; const f32x2 vv2 = {vv, vv};
;                 const float xk = sv[1 * 64 + lane], xb = sv[2 * 64 + lane], xr = sv[5 * 64 + lane];
;                 float qd0 = 0.f, qd1 = 0.f, qd2 = 0.f, qd3 = 0.f, pd0 = 0.f, pd1 = 0.f, pd2 = 0.f, pd3 = 0.f, yd0 = 0.f, yd1 = 0.f, yd2 = 0.f, yd3 = 0.f, zd0 = 0.f, zd1 = 0.f, zd2 = 0.f, zd3 = 0.f;
;                 const int l15 = lane & 15; float xkq0 = sv[64 + l15], xkq1 = sv[64 + 16 + l15], xkq2 = sv[64 + 32 + l15], xkq3 = sv[64 + 48 + l15], xrq0 = sv[320 + l15], xrq1 = sv[320 + 16 + l15], xrq2 = sv[320 + 32 + l15], xrq3 = sv[320 + 48 + l15];
;     ...
;                 __builtin_amdgcn_sched_barrier(0);
;                 DPPFMAC(qd0, xkq0, Q2[0].x, 0); DPPFMAC(pd0, xkq0, P2[0].x, 0);
;                 DPPFMAC(qd1, xkq0, Q2[0].y, 1); DPPFMAC(pd1, xkq0, P2[0].y, 1);
;                 DPPFMAC(qd2, xkq0, Q2[1].x, 2); DPPFMAC(pd2, xkq0, P2[1].x, 2);
;                 DPPFMAC(qd3, xkq0, Q2[1].y, 3); DPPFMAC(pd3, xkq0, P2[1].y, 3);
;                 DPPFMAC(qd0, xkq0, Q2[2].x, 4); DPPFMAC(pd0, xkq0, P2[2].x, 4);
;                 DPPFMAC(qd1, xkq0, Q2[2].y, 5); DPPFMAC(pd1, xkq0, P2[2].y, 5);
;                 DPPFMAC(qd2, xkq0, Q2[3].x, 6); DPPFMAC(pd2, xkq0, P2[3].x, 6);
;                 DPPFMAC(qd3, xkq0, Q2[3].y, 7); DPPFMAC(pd3, xkq0, P2[3].y, 7);
;                 DPPFMAC(qd0, xkq0, Q2[4].x, 8); DPPFMAC(pd0, xkq0, P2[4].x, 8);
;                 DPPFMAC(qd1, xkq0, Q2[4].y, 9); DPPFMAC(pd1, xkq0, P2[4].y, 9);
;                 DPPFMAC(qd2, xkq0, Q2[5].x, 10); DPPFMAC(pd2, xkq0, P2[5].x, 10);
;                 DPPFMAC(qd3, xkq0, Q2[5].y, 11); DPPFMAC(pd3, xkq0, P2[5].y, 11);
;                 DPPFMAC(qd0, xkq0, Q2[6].x, 12); DPPFMAC(pd0, xkq0, P2[6].x, 12);
;                 DPPFMAC(qd1, xkq0, Q2[6].y, 13); DPPFMAC(pd1, xkq0, P2[6].y, 13);
;                 DPPFMAC(qd2, xkq0, Q2[7].x, 14); DPPFMAC(pd2, xkq0, P2[7].x, 14);
;                 DPPFMAC(qd3, xkq0, Q2[7].y, 15); DPPFMAC(pd3, xkq0, P2[7].y, 15);
;                 __builtin_amdgcn_sched_barrier(0);
.Lp5_norenorm:
	v_and_b32_e32 v255, 0xc0, v245
	v_add_u32_e32 v255, v255, v158
	v_add_u32_e32 v247, v245, v158
	ds_read_b32 v224, v247 offset:0
	ds_read_b32 v225, v247 offset:256
	ds_read_b32 v226, v247 offset:512
	ds_read_b32 v227, v247 offset:768
	ds_read_b32 v228, v247 offset:1280
	ds_read_b32 v229, v247 offset:1536
	ds_read_b32 v230, v247 offset:1792
	ds_read_b32 v231, v247 offset:2048
	ds_read_b32 v232, v247 offset:2304
	ds_read_b32 v233, v247 offset:2816
	s_waitcnt lgkmcnt(0)
	v_mul_f32_e32 v225, v225, v246
	v_mul_f32_e32 v246, v246, v224
	v_rcp_f32_e32 v234, v246
	v_mul_f32_e32 v228, v228, v246
	ds_write_b32 v247, v225 offset:256
	v_mul_f32_e32 v226, v226, v234
	v_mul_f32_e32 v227, v227, v234
	ds_write_b32 v247, v228 offset:1280
	ds_write_b32 v247, v226 offset:512
	ds_write_b32 v247, v227 offset:768
	v_mul_f32_e32 v230, v230, v246
	v_mul_f32_e32 v246, v246, v229
	v_rcp_f32_e32 v235, v246
	v_mul_f32_e32 v233, v233, v246
	ds_write_b32 v247, v230 offset:1792
	v_mul_f32_e32 v231, v231, v235
	v_mul_f32_e32 v232, v232, v235
	ds_write_b32 v247, v233 offset:2816
	ds_write_b32 v247, v231 offset:2048
	ds_write_b32 v247, v232 offset:2304
	s_waitcnt lgkmcnt(3)
	ds_read_b32 v224, v247 offset:3072
	ds_read_b32 v225, v247 offset:3328
	ds_read_b32 v226, v247 offset:3584
	ds_read_b32 v227, v247 offset:3840
	ds_read_b32 v228, v247 offset:4352
	ds_read_b32 v229, v247 offset:4608
	ds_read_b32 v230, v247 offset:4864
	ds_read_b32 v231, v247 offset:5120
	ds_read_b32 v232, v247 offset:5376
	ds_read_b32 v233, v247 offset:5888
	s_waitcnt lgkmcnt(0)
	v_mul_f32_e32 v225, v225, v246
	v_mul_f32_e32 v246, v246, v224
	v_rcp_f32_e32 v234, v246
	v_mul_f32_e32 v228, v228, v246
	ds_write_b32 v247, v225 offset:3328
	v_mul_f32_e32 v226, v226, v234
	v_mul_f32_e32 v227, v227, v234
	ds_write_b32 v247, v228 offset:4352
	ds_write_b32 v247, v226 offset:3584
	ds_write_b32 v247, v227 offset:3840
	v_mul_f32_e32 v230, v230, v246
	v_mul_f32_e32 v246, v246, v229
	v_rcp_f32_e32 v235, v246
	v_mul_f32_e32 v233, v233, v246
	ds_write_b32 v247, v230 offset:4864
	v_mul_f32_e32 v231, v231, v235
	v_mul_f32_e32 v232, v232, v235
	ds_write_b32 v247, v233 offset:5888
	ds_write_b32 v247, v231 offset:5120
	ds_write_b32 v247, v232 offset:5376
	ds_read_b128 v[192:195], v255 offset:256
	ds_read_b128 v[196:199], v255 offset:272
	ds_read_b128 v[200:203], v255 offset:288
	ds_read_b128 v[204:207], v255 offset:304
	s_waitcnt lgkmcnt(4)
	ds_read_b128 v[224:227], v255 offset:512
	ds_read_b128 v[228:231], v255 offset:528
	ds_read_b128 v[232:235], v255 offset:544
	ds_read_b128 v[236:239], v255 offset:560
	ds_read_b128 v[240:243], v255 offset:768
	ds_read_b128 v[166:169], v255 offset:784
	ds_read_b128 v[170:173], v255 offset:800
	ds_read_b128 v[174:177], v255 offset:816
	ds_read_b32 v254, v247 offset:1024
.Lp5_step:
	s_waitcnt lgkmcnt(0)
	v_mul_f32_e32 v208, v0, v192
	v_mul_f32_e32 v212, v64, v192
	v_mul_f32_e32 v209, v1, v192
	v_mul_f32_e32 v213, v65, v192
	v_mul_f32_e32 v210, v2, v192
	v_mul_f32_e32 v214, v66, v192
	v_mul_f32_e32 v211, v3, v192
	v_mul_f32_e32 v215, v67, v192
	v_fmac_f32_e32 v208, v4, v193
	v_fmac_f32_e32 v212, v68, v193
	v_fmac_f32_e32 v209, v5, v193
	v_fmac_f32_e32 v213, v69, v193
	v_fmac_f32_e32 v210, v6, v193
	v_fmac_f32_e32 v214, v70, v193
	v_fmac_f32_e32 v211, v7, v193
	v_fmac_f32_e32 v215, v71, v193
	v_fmac_f32_e32 v208, v8, v194
	v_fmac_f32_e32 v212, v72, v194
	v_fmac_f32_e32 v209, v9, v194
	v_fmac_f32_e32 v213, v73, v194
	v_fmac_f32_e32 v210, v10, v194
	v_fmac_f32_e32 v214, v74, v194
	v_fmac_f32_e32 v211, v11, v194
	v_fmac_f32_e32 v215, v75, v194
	v_fmac_f32_e32 v208, v12, v195
	v_fmac_f32_e32 v212, v76, v195
	v_fmac_f32_e32 v209, v13, v195
	v_fmac_f32_e32 v213, v77, v195
	v_fmac_f32_e32 v210, v14, v195
	v_fmac_f32_e32 v214, v78, v195
	v_fmac_f32_e32 v211, v15, v195
	v_fmac_f32_e32 v215, v79, v195
	v_fmac_f32_e32 v208, v16, v196
	v_fmac_f32_e32 v212, v80, v196
	v_fmac_f32_e32 v209, v17, v196
	v_fmac_f32_e32 v213, v81, v196
	v_fmac_f32_e32 v210, v18, v196
	v_fmac_f32_e32 v214, v82, v196
	v_fmac_f32_e32 v211, v19, v196
	v_fmac_f32_e32 v215, v83, v196
	v_fmac_f32_e32 v208, v20, v197
	v_fmac_f32_e32 v212, v84, v197
	v_fmac_f32_e32 v209, v21, v197
	v_fmac_f32_e32 v213, v85, v197
	v_fmac_f32_e32 v210, v22, v197
	v_fmac_f32_e32 v214, v86, v197
	v_fmac_f32_e32 v211, v23, v197
	v_fmac_f32_e32 v215, v87, v197
	v_fmac_f32_e32 v208, v24, v198
	v_fmac_f32_e32 v212, v88, v198
	v_fmac_f32_e32 v209, v25, v198
	v_fmac_f32_e32 v213, v89, v198
	v_fmac_f32_e32 v210, v26, v198
	v_fmac_f32_e32 v214, v90, v198
	v_fmac_f32_e32 v211, v27, v198
	v_fmac_f32_e32 v215, v91, v198
	v_fmac_f32_e32 v208, v28, v199
	v_fmac_f32_e32 v212, v92, v199
	v_fmac_f32_e32 v209, v29, v199
	v_fmac_f32_e32 v213, v93, v199
	v_fmac_f32_e32 v210, v30, v199
	v_fmac_f32_e32 v214, v94, v199
	v_fmac_f32_e32 v211, v31, v199
	v_fmac_f32_e32 v215, v95, v199
	v_fmac_f32_e32 v208, v32, v200
	v_fmac_f32_e32 v212, v96, v200
	v_fmac_f32_e32 v209, v33, v200
	v_fmac_f32_e32 v213, v97, v200
	v_fmac_f32_e32 v210, v34, v200
	v_fmac_f32_e32 v214, v98, v200
	v_fmac_f32_e32 v211, v35, v200
	v_fmac_f32_e32 v215, v99, v200
	v_fmac_f32_e32 v208, v36, v201
	v_fmac_f32_e32 v212, v100, v201
	v_fmac_f32_e32 v209, v37, v201
	v_fmac_f32_e32 v213, v101, v201
	v_fmac_f32_e32 v210, v38, v201
	v_fmac_f32_e32 v214, v102, v201
	v_fmac_f32_e32 v211, v39, v201
	v_fmac_f32_e32 v215, v103, v201
	v_fmac_f32_e32 v208, v40, v202
	v_fmac_f32_e32 v212, v104, v202
	v_fmac_f32_e32 v209, v41, v202
	v_fmac_f32_e32 v213, v105, v202
	v_fmac_f32_e32 v210, v42, v202
	v_fmac_f32_e32 v214, v106, v202
	v_fmac_f32_e32 v211, v43, v202
	v_fmac_f32_e32 v215, v107, v202
;     ...
;                 DPPFMAC(qd0, xkq3, Q2[24].x, 0); DPPFMAC(pd0, xkq3, P2[24].x, 0);
;                 DPPFMAC(qd1, xkq3, Q2[24].y, 1); DPPFMAC(pd1, xkq3, P2[24].y, 1);
;                 DPPFMAC(qd2, xkq3, Q2[25].x, 2); DPPFMAC(pd2, xkq3, P2[25].x, 2);
;                 DPPFMAC(qd3, xkq3, Q2[25].y, 3); DPPFMAC(pd3, xkq3, P2[25].y, 3);
;                 DPPFMAC(qd0, xkq3, Q2[26].x, 4); DPPFMAC(pd0, xkq3, P2[26].x, 4);
;                 DPPFMAC(qd1, xkq3, Q2[26].y, 5); DPPFMAC(pd1, xkq3, P2[26].y, 5);
;                 DPPFMAC(qd2, xkq3, Q2[27].x, 6); DPPFMAC(pd2, xkq3, P2[27].x, 6);
;                 DPPFMAC(qd3, xkq3, Q2[27].y, 7); DPPFMAC(pd3, xkq3, P2[27].y, 7);
;                 DPPFMAC(qd0, xkq3, Q2[28].x, 8); DPPFMAC(pd0, xkq3, P2[28].x, 8);
;                 DPPFMAC(qd1, xkq3, Q2[28].y, 9); DPPFMAC(pd1, xkq3, P2[28].y, 9);
;                 DPPFMAC(qd2, xkq3, Q2[29].x, 10); DPPFMAC(pd2, xkq3, P2[29].x, 10);
;                 DPPFMAC(qd3, xkq3, Q2[29].y, 11); DPPFMAC(pd3, xkq3, P2[29].y, 11);
;                 DPPFMAC(qd0, xkq3, Q2[30].x, 12); DPPFMAC(pd0, xkq3, P2[30].x, 12);
;                 DPPFMAC(qd1, xkq3, Q2[30].y, 13); DPPFMAC(pd1, xkq3, P2[30].y, 13);
;                 DPPFMAC(qd2, xkq3, Q2[31].x, 14); DPPFMAC(pd2, xkq3, P2[31].x, 14);
;                 DPPFMAC(qd3, xkq3, Q2[31].y, 15); DPPFMAC(pd3, xkq3, P2[31].y, 15);
;                 { const float saq = -((qd0 + qd1) + (qd2 + qd3)), sap = -((pd0 + pd1) + (pd2 + pd3)); saq2 = (f32x2){saq, saq}; sap2 = (f32x2){sap, sap}; }
;                 __builtin_amdgcn_sched_barrier(0);
;                 f32x4 d_2 = L4[2], b_2 = L4[34], k_2 = L4[50];
;                 f32x4 d_3 = L4[3], b_3 = L4[35], k_3 = L4[51];
;                 asm volatile("s_nop 1" : "+v"(xrq0), "+v"(xrq1), "+v"(xrq2), "+v"(xrq3));
;                 { const f32x2 bxy = b_0.xy, bzw = b_0.zw;
;                 Q2[0] = Q2[0] * d_0.xy + (saq2 * bxy + vv2 * k_0.xy); Q2[1] = Q2[1] * d_0.zw + (saq2 * bzw + vv2 * k_0.zw);
;                 P2[0] = P2[0] * d_0.xy + sap2 * bxy; P2[1] = P2[1] * d_0.zw + sap2 * bzw;
;                 DPPFMAC(yd0, xrq0, Q2[0].x, 0); DPPFMAC(zd0, xrq0, P2[0].x, 0);
;                 DPPFMAC(yd1, xrq0, Q2[0].y, 1); DPPFMAC(zd1, xrq0, P2[0].y, 1);
;                 DPPFMAC(yd2, xrq0, Q2[1].x, 2); DPPFMAC(zd2, xrq0, P2[1].x, 2);
;                 DPPFMAC(yd3, xrq0, Q2[1].y, 3); DPPFMAC(zd3, xrq0, P2[1].y, 3);
	v_fmac_f32_e32 v208, v44, v203
	v_fmac_f32_e32 v212, v108, v203
	v_fmac_f32_e32 v209, v45, v203
	v_fmac_f32_e32 v213, v109, v203
	v_fmac_f32_e32 v210, v46, v203
	v_fmac_f32_e32 v214, v110, v203
	v_fmac_f32_e32 v211, v47, v203
	v_fmac_f32_e32 v215, v111, v203
	v_fmac_f32_e32 v208, v48, v204
	v_fmac_f32_e32 v212, v112, v204
	v_fmac_f32_e32 v209, v49, v204
	v_fmac_f32_e32 v213, v113, v204
	v_fmac_f32_e32 v210, v50, v204
	v_fmac_f32_e32 v214, v114, v204
	v_fmac_f32_e32 v211, v51, v204
	v_fmac_f32_e32 v215, v115, v204
	v_fmac_f32_e32 v208, v52, v205
	v_fmac_f32_e32 v212, v116, v205
	v_fmac_f32_e32 v209, v53, v205
	v_fmac_f32_e32 v213, v117, v205
	v_fmac_f32_e32 v210, v54, v205
	v_fmac_f32_e32 v214, v118, v205
	v_fmac_f32_e32 v211, v55, v205
	v_fmac_f32_e32 v215, v119, v205
	v_fmac_f32_e32 v208, v56, v206
	v_fmac_f32_e32 v212, v120, v206
	v_fmac_f32_e32 v209, v57, v206
	v_fmac_f32_e32 v213, v121, v206
	v_fmac_f32_e32 v210, v58, v206
	v_fmac_f32_e32 v214, v122, v206
	v_fmac_f32_e32 v211, v59, v206
	v_fmac_f32_e32 v215, v123, v206
	v_fmac_f32_e32 v208, v60, v207
	v_fmac_f32_e32 v212, v124, v207
	v_fmac_f32_e32 v209, v61, v207
	v_fmac_f32_e32 v213, v125, v207
	v_fmac_f32_e32 v210, v62, v207
	v_fmac_f32_e32 v214, v126, v207
	v_fmac_f32_e32 v211, v63, v207
	v_fmac_f32_e32 v215, v127, v207
	ds_read_b128 v[192:195], v255 offset:1280
	ds_read_b128 v[196:199], v255 offset:1296
	ds_read_b128 v[200:203], v255 offset:1312
	ds_read_b128 v[204:207], v255 offset:1328
	v_add_f32_dpp v208, v208, v208 quad_perm:[1,0,3,2] row_mask:0xf bank_mask:0xf
	v_add_f32_dpp v209, v209, v209 quad_perm:[1,0,3,2] row_mask:0xf bank_mask:0xf
	v_add_f32_dpp v210, v210, v210 quad_perm:[1,0,3,2] row_mask:0xf bank_mask:0xf
	v_add_f32_dpp v211, v211, v211 quad_perm:[1,0,3,2] row_mask:0xf bank_mask:0xf
	v_add_f32_dpp v212, v212, v212 quad_perm:[1,0,3,2] row_mask:0xf bank_mask:0xf
	v_add_f32_dpp v213, v213, v213 quad_perm:[1,0,3,2] row_mask:0xf bank_mask:0xf
	v_add_f32_dpp v214, v214, v214 quad_perm:[1,0,3,2] row_mask:0xf bank_mask:0xf
	v_add_f32_dpp v215, v215, v215 quad_perm:[1,0,3,2] row_mask:0xf bank_mask:0xf
	v_add_f32_dpp v208, v208, v208 quad_perm:[2,3,0,1] row_mask:0xf bank_mask:0xf
	v_add_f32_dpp v209, v209, v209 quad_perm:[2,3,0,1] row_mask:0xf bank_mask:0xf
	v_add_f32_dpp v210, v210, v210 quad_perm:[2,3,0,1] row_mask:0xf bank_mask:0xf
	v_add_f32_dpp v211, v211, v211 quad_perm:[2,3,0,1] row_mask:0xf bank_mask:0xf
	v_add_f32_dpp v212, v212, v212 quad_perm:[2,3,0,1] row_mask:0xf bank_mask:0xf
	v_add_f32_dpp v213, v213, v213 quad_perm:[2,3,0,1] row_mask:0xf bank_mask:0xf
	v_add_f32_dpp v214, v214, v214 quad_perm:[2,3,0,1] row_mask:0xf bank_mask:0xf
	v_add_f32_dpp v215, v215, v215 quad_perm:[2,3,0,1] row_mask:0xf bank_mask:0xf
	v_cndmask_b32_e64 v178, -v208, -v209, s[86:87]
	v_cndmask_b32_e64 v179, -v212, -v213, s[86:87]
	v_cndmask_b32_e64 v178, v178, -v210, s[88:89]
	v_cndmask_b32_e64 v179, v179, -v214, s[88:89]
	v_cndmask_b32_e64 v178, v178, -v211, s[84:85]
	v_cndmask_b32_e64 v179, v179, -v215, s[84:85]
	s_nop 1
	v_mfma_f32_4x4x1_16b_f32 v[0:3], v178, v224, v[0:3]
	v_mfma_f32_4x4x1_16b_f32 v[64:67], v179, v224, v[64:67]
	v_mfma_f32_4x4x1_16b_f32 v[4:7], v178, v225, v[4:7]
	v_mfma_f32_4x4x1_16b_f32 v[68:71], v179, v225, v[68:71]
	v_mfma_f32_4x4x1_16b_f32 v[0:3], v254, v240, v[0:3]
	v_mfma_f32_4x4x1_16b_f32 v[8:11], v178, v226, v[8:11]
	v_mfma_f32_4x4x1_16b_f32 v[72:75], v179, v226, v[72:75]
	v_mfma_f32_4x4x1_16b_f32 v[4:7], v254, v241, v[4:7]
	s_waitcnt lgkmcnt(0)
	v_mfma_f32_4x4x1_16b_f32 v[12:15], v178, v227, v[12:15]
	v_mul_f32_e32 v208, v0, v192
	v_mul_f32_e32 v212, v64, v192
	v_mul_f32_e32 v209, v1, v192
	v_mul_f32_e32 v213, v65, v192
	v_mfma_f32_4x4x1_16b_f32 v[76:79], v179, v227, v[76:79]
	v_mul_f32_e32 v210, v2, v192
	v_mul_f32_e32 v214, v66, v192
	v_mul_f32_e32 v211, v3, v192
	v_mul_f32_e32 v215, v67, v192
	v_mfma_f32_4x4x1_16b_f32 v[8:11], v254, v242, v[8:11]
	v_mfma_f32_4x4x1_16b_f32 v[16:19], v178, v228, v[16:19]
	v_fmac_f32_e32 v208, v4, v193
	v_fmac_f32_e32 v212, v68, v193
	v_fmac_f32_e32 v209, v5, v193
	v_fmac_f32_e32 v213, v69, v193
	v_mfma_f32_4x4x1_16b_f32 v[80:83], v179, v228, v[80:83]
	v_fmac_f32_e32 v210, v6, v193
	v_fmac_f32_e32 v214, v70, v193
	v_fmac_f32_e32 v211, v7, v193
	v_fmac_f32_e32 v215, v71, v193
	v_mfma_f32_4x4x1_16b_f32 v[12:15], v254, v243, v[12:15]
	v_mfma_f32_4x4x1_16b_f32 v[20:23], v178, v229, v[20:23]
	v_fmac_f32_e32 v208, v8, v194
	v_fmac_f32_e32 v212, v72, v194
	v_fmac_f32_e32 v209, v9, v194
	v_fmac_f32_e32 v213, v73, v194
	v_mfma_f32_4x4x1_16b_f32 v[84:87], v179, v229, v[84:87]
	v_fmac_f32_e32 v210, v10, v194
	v_fmac_f32_e32 v214, v74, v194
	v_fmac_f32_e32 v211, v11, v194
	v_fmac_f32_e32 v215, v75, v194
	v_mfma_f32_4x4x1_16b_f32 v[16:19], v254, v166, v[16:19]
	v_mfma_f32_4x4x1_16b_f32 v[24:27], v178, v230, v[24:27]
	v_fmac_f32_e32 v208, v12, v195
	v_fmac_f32_e32 v212, v76, v195
	v_fmac_f32_e32 v209, v13, v195
	v_fmac_f32_e32 v213, v77, v195
	v_mfma_f32_4x4x1_16b_f32 v[88:91], v179, v230, v[88:91]
	v_fmac_f32_e32 v210, v14, v195
	v_fmac_f32_e32 v214, v78, v195
	v_fmac_f32_e32 v211, v15, v195
	v_fmac_f32_e32 v215, v79, v195
	v_mfma_f32_4x4x1_16b_f32 v[20:23], v254, v167, v[20:23]
	v_mfma_f32_4x4x1_16b_f32 v[28:31], v178, v231, v[28:31]
	v_fmac_f32_e32 v208, v16, v196
	v_fmac_f32_e32 v212, v80, v196
	v_fmac_f32_e32 v209, v17, v196
	v_fmac_f32_e32 v213, v81, v196
	v_mfma_f32_4x4x1_16b_f32 v[92:95], v179, v231, v[92:95]
	v_fmac_f32_e32 v210, v18, v196
	v_fmac_f32_e32 v214, v82, v196
	v_fmac_f32_e32 v211, v19, v196
	v_fmac_f32_e32 v215, v83, v196
	v_mfma_f32_4x4x1_16b_f32 v[24:27], v254, v168, v[24:27]
	v_mfma_f32_4x4x1_16b_f32 v[32:35], v178, v232, v[32:35]
;     ...
;                 { const f32x2 bxy = b_12.xy, bzw = b_12.zw;
;                 Q2[24] = Q2[24] * d_12.xy + (saq2 * bxy + vv2 * k_12.xy); Q2[25] = Q2[25] * d_12.zw + (saq2 * bzw + vv2 * k_12.zw);
;                 P2[24] = P2[24] * d_12.xy + sap2 * bxy; P2[25] = P2[25] * d_12.zw + sap2 * bzw;
;                 DPPFMAC(yd0, xrq3, Q2[24].x, 0); DPPFMAC(zd0, xrq3, P2[24].x, 0);
;                 DPPFMAC(yd1, xrq3, Q2[24].y, 1); DPPFMAC(zd1, xrq3, P2[24].y, 1);
;                 DPPFMAC(yd2, xrq3, Q2[25].x, 2); DPPFMAC(zd2, xrq3, P2[25].x, 2);
;                 DPPFMAC(yd3, xrq3, Q2[25].y, 3); DPPFMAC(zd3, xrq3, P2[25].y, 3);
;                 }
;                 { const f32x2 bxy = b_13.xy, bzw = b_13.zw;
;                 Q2[26] = Q2[26] * d_13.xy + (saq2 * bxy + vv2 * k_13.xy); Q2[27] = Q2[27] * d_13.zw + (saq2 * bzw + vv2 * k_13.zw);
;                 P2[26] = P2[26] * d_13.xy + sap2 * bxy; P2[27] = P2[27] * d_13.zw + sap2 * bzw;
;                 DPPFMAC(yd0, xrq3, Q2[26].x, 4); DPPFMAC(zd0, xrq3, P2[26].x, 4);
;                 DPPFMAC(yd1, xrq3, Q2[26].y, 5); DPPFMAC(zd1, xrq3, P2[26].y, 5);
;                 DPPFMAC(yd2, xrq3, Q2[27].x, 6); DPPFMAC(zd2, xrq3, P2[27].x, 6);
;                 DPPFMAC(yd3, xrq3, Q2[27].y, 7); DPPFMAC(zd3, xrq3, P2[27].y, 7);
;                 }
;                 __builtin_amdgcn_sched_barrier(0);
;                 { const f32x2 bxy = b_14.xy, bzw = b_14.zw;
;                 Q2[28] = Q2[28] * d_14.xy + (saq2 * bxy + vv2 * k_14.xy); Q2[29] = Q2[29] * d_14.zw + (saq2 * bzw + vv2 * k_14.zw);
;                 P2[28] = P2[28] * d_14.xy + sap2 * bxy; P2[29] = P2[29] * d_14.zw + sap2 * bzw;
;                 DPPFMAC(yd0, xrq3, Q2[28].x, 8); DPPFMAC(zd0, xrq3, P2[28].x, 8);
;                 DPPFMAC(yd1, xrq3, Q2[28].y, 9); DPPFMAC(zd1, xrq3, P2[28].y, 9);
;                 DPPFMAC(yd2, xrq3, Q2[29].x, 10); DPPFMAC(zd2, xrq3, P2[29].x, 10);
;                 DPPFMAC(yd3, xrq3, Q2[29].y, 11); DPPFMAC(zd3, xrq3, P2[29].y, 11);
;                 }
;                 { const f32x2 bxy = b_15.xy, bzw = b_15.zw;
;                 Q2[30] = Q2[30] * d_15.xy + (saq2 * bxy + vv2 * k_15.xy); Q2[31] = Q2[31] * d_15.zw + (saq2 * bzw + vv2 * k_15.zw);
;                 P2[30] = P2[30] * d_15.xy + sap2 * bxy; P2[31] = P2[31] * d_15.zw + sap2 * bzw;
;                 DPPFMAC(yd0, xrq3, Q2[30].x, 12); DPPFMAC(zd0, xrq3, P2[30].x, 12);
	v_fmac_f32_e32 v208, v20, v197
	v_fmac_f32_e32 v212, v84, v197
	v_fmac_f32_e32 v209, v21, v197
	v_fmac_f32_e32 v213, v85, v197
	v_mfma_f32_4x4x1_16b_f32 v[96:99], v179, v232, v[96:99]
	v_fmac_f32_e32 v210, v22, v197
	v_fmac_f32_e32 v214, v86, v197
	v_fmac_f32_e32 v211, v23, v197
	v_fmac_f32_e32 v215, v87, v197
	v_mfma_f32_4x4x1_16b_f32 v[28:31], v254, v169, v[28:31]
	v_mfma_f32_4x4x1_16b_f32 v[36:39], v178, v233, v[36:39]
	v_fmac_f32_e32 v208, v24, v198
	v_fmac_f32_e32 v212, v88, v198
	v_fmac_f32_e32 v209, v25, v198
	v_fmac_f32_e32 v213, v89, v198
	v_mfma_f32_4x4x1_16b_f32 v[100:103], v179, v233, v[100:103]
	v_fmac_f32_e32 v210, v26, v198
	v_fmac_f32_e32 v214, v90, v198
	v_fmac_f32_e32 v211, v27, v198
	v_fmac_f32_e32 v215, v91, v198
	v_mfma_f32_4x4x1_16b_f32 v[32:35], v254, v170, v[32:35]
	v_mfma_f32_4x4x1_16b_f32 v[40:43], v178, v234, v[40:43]
	v_fmac_f32_e32 v208, v28, v199
	v_fmac_f32_e32 v212, v92, v199
	v_fmac_f32_e32 v209, v29, v199
	v_fmac_f32_e32 v213, v93, v199
	v_mfma_f32_4x4x1_16b_f32 v[104:107], v179, v234, v[104:107]
	v_fmac_f32_e32 v210, v30, v199
	v_fmac_f32_e32 v214, v94, v199
	v_fmac_f32_e32 v211, v31, v199
	v_fmac_f32_e32 v215, v95, v199
	v_mfma_f32_4x4x1_16b_f32 v[36:39], v254, v171, v[36:39]
	v_mfma_f32_4x4x1_16b_f32 v[44:47], v178, v235, v[44:47]
	v_fmac_f32_e32 v208, v32, v200
	v_fmac_f32_e32 v212, v96, v200
	v_fmac_f32_e32 v209, v33, v200
	v_fmac_f32_e32 v213, v97, v200
	v_mfma_f32_4x4x1_16b_f32 v[108:111], v179, v235, v[108:111]
	v_fmac_f32_e32 v210, v34, v200
	v_fmac_f32_e32 v214, v98, v200
	v_fmac_f32_e32 v211, v35, v200
	v_fmac_f32_e32 v215, v99, v200
	v_mfma_f32_4x4x1_16b_f32 v[40:43], v254, v172, v[40:43]
	v_mfma_f32_4x4x1_16b_f32 v[48:51], v178, v236, v[48:51]
	v_fmac_f32_e32 v208, v36, v201
	v_fmac_f32_e32 v212, v100, v201
	v_fmac_f32_e32 v209, v37, v201
	v_fmac_f32_e32 v213, v101, v201
	v_mfma_f32_4x4x1_16b_f32 v[112:115], v179, v236, v[112:115]
	v_fmac_f32_e32 v210, v38, v201
	v_fmac_f32_e32 v214, v102, v201
	v_fmac_f32_e32 v211, v39, v201
	v_fmac_f32_e32 v215, v103, v201
	v_mfma_f32_4x4x1_16b_f32 v[44:47], v254, v173, v[44:47]
	v_mfma_f32_4x4x1_16b_f32 v[52:55], v178, v237, v[52:55]
	v_fmac_f32_e32 v208, v40, v202
	v_fmac_f32_e32 v212, v104, v202
	v_fmac_f32_e32 v209, v41, v202
	v_fmac_f32_e32 v213, v105, v202
	v_mfma_f32_4x4x1_16b_f32 v[116:119], v179, v237, v[116:119]
	v_fmac_f32_e32 v210, v42, v202
	v_fmac_f32_e32 v214, v106, v202
	v_fmac_f32_e32 v211, v43, v202
	v_fmac_f32_e32 v215, v107, v202
	v_mfma_f32_4x4x1_16b_f32 v[48:51], v254, v174, v[48:51]
	v_mfma_f32_4x4x1_16b_f32 v[56:59], v178, v238, v[56:59]
	v_fmac_f32_e32 v208, v44, v203
	v_fmac_f32_e32 v212, v108, v203
	v_fmac_f32_e32 v209, v45, v203
	v_fmac_f32_e32 v213, v109, v203
	v_mfma_f32_4x4x1_16b_f32 v[120:123], v179, v238, v[120:123]
	v_fmac_f32_e32 v210, v46, v203
	v_fmac_f32_e32 v214, v110, v203
	v_fmac_f32_e32 v211, v47, v203
	v_fmac_f32_e32 v215, v111, v203
	v_mfma_f32_4x4x1_16b_f32 v[52:55], v254, v175, v[52:55]
	v_mfma_f32_4x4x1_16b_f32 v[60:63], v178, v239, v[60:63]
	v_fmac_f32_e32 v208, v48, v204
	v_fmac_f32_e32 v212, v112, v204
	v_fmac_f32_e32 v209, v49, v204
	v_fmac_f32_e32 v213, v113, v204
	v_mfma_f32_4x4x1_16b_f32 v[124:127], v179, v239, v[124:127]
	v_fmac_f32_e32 v210, v50, v204
	v_fmac_f32_e32 v214, v114, v204
	v_fmac_f32_e32 v211, v51, v204
	v_fmac_f32_e32 v215, v115, v204
	v_mfma_f32_4x4x1_16b_f32 v[56:59], v254, v176, v[56:59]
	v_fmac_f32_e32 v208, v52, v205
	v_fmac_f32_e32 v212, v116, v205
	v_fmac_f32_e32 v209, v53, v205
	v_fmac_f32_e32 v213, v117, v205
	v_fmac_f32_e32 v210, v54, v205
	v_fmac_f32_e32 v214, v118, v205
	v_fmac_f32_e32 v211, v55, v205
	v_fmac_f32_e32 v215, v119, v205
	v_mfma_f32_4x4x1_16b_f32 v[60:63], v254, v177, v[60:63]
	ds_read_b128 v[224:227], v255 offset:2048
	ds_read_b128 v[228:231], v255 offset:2064
	ds_read_b128 v[232:235], v255 offset:2080
	ds_read_b128 v[236:239], v255 offset:2096
	ds_read_b128 v[240:243], v255 offset:2304
	ds_read_b128 v[166:169], v255 offset:2320
	ds_read_b128 v[170:173], v255 offset:2336
	ds_read_b128 v[174:177], v255 offset:2352
	ds_read_b32 v254, v247 offset:2560
	v_fmac_f32_e32 v208, v56, v206
	v_fmac_f32_e32 v212, v120, v206
	v_fmac_f32_e32 v209, v57, v206
	v_fmac_f32_e32 v213, v121, v206
	v_fmac_f32_e32 v210, v58, v206
	v_fmac_f32_e32 v214, v122, v206
	v_fmac_f32_e32 v211, v59, v206
	v_fmac_f32_e32 v215, v123, v206
	v_fmac_f32_e32 v208, v60, v207
	v_fmac_f32_e32 v212, v124, v207
	v_fmac_f32_e32 v209, v61, v207
	v_fmac_f32_e32 v213, v125, v207
	v_fmac_f32_e32 v210, v62, v207
	v_fmac_f32_e32 v214, v126, v207
	v_fmac_f32_e32 v211, v63, v207
	v_fmac_f32_e32 v215, v127, v207
	ds_read_b128 v[192:195], v255 offset:1792
	ds_read_b128 v[196:199], v255 offset:1808
	ds_read_b128 v[200:203], v255 offset:1824
	ds_read_b128 v[204:207], v255 offset:1840
	v_add_f32_dpp v208, v208, v208 quad_perm:[1,0,3,2] row_mask:0xf bank_mask:0xf
	v_add_f32_dpp v209, v209, v209 quad_perm:[1,0,3,2] row_mask:0xf bank_mask:0xf
	v_add_f32_dpp v210, v210, v210 quad_perm:[1,0,3,2] row_mask:0xf bank_mask:0xf
	v_add_f32_dpp v211, v211, v211 quad_perm:[1,0,3,2] row_mask:0xf bank_mask:0xf
	v_add_f32_dpp v212, v212, v212 quad_perm:[1,0,3,2] row_mask:0xf bank_mask:0xf
	v_add_f32_dpp v213, v213, v213 quad_perm:[1,0,3,2] row_mask:0xf bank_mask:0xf
	v_add_f32_dpp v214, v214, v214 quad_perm:[1,0,3,2] row_mask:0xf bank_mask:0xf
	v_add_f32_dpp v215, v215, v215 quad_perm:[1,0,3,2] row_mask:0xf bank_mask:0xf
	v_add_f32_dpp v208, v208, v208 quad_perm:[2,3,0,1] row_mask:0xf bank_mask:0xf
	v_add_f32_dpp v209, v209, v209 quad_perm:[2,3,0,1] row_mask:0xf bank_mask:0xf
	v_add_f32_dpp v210, v210, v210 quad_perm:[2,3,0,1] row_mask:0xf bank_mask:0xf
	v_add_f32_dpp v211, v211, v211 quad_perm:[2,3,0,1] row_mask:0xf bank_mask:0xf
	v_add_f32_dpp v212, v212, v212 quad_perm:[2,3,0,1] row_mask:0xf bank_mask:0xf
	v_add_f32_dpp v213, v213, v213 quad_perm:[2,3,0,1] row_mask:0xf bank_mask:0xf
	v_add_f32_dpp v214, v214, v214 quad_perm:[2,3,0,1] row_mask:0xf bank_mask:0xf
	v_add_f32_dpp v215, v215, v215 quad_perm:[2,3,0,1] row_mask:0xf bank_mask:0xf
	v_cndmask_b32_e64 v178, v208, v209, s[86:87]
	v_cndmask_b32_e64 v179, v212, v213, s[86:87]
	v_cndmask_b32_e64 v178, v178, v210, s[88:89]
	v_cndmask_b32_e64 v179, v179, v214, s[88:89]
	v_cndmask_b32_e64 v178, v178, v211, s[84:85]
	v_cndmask_b32_e64 v179, v179, v215, s[84:85]
	v_add_u32_e32 v130, s45, v141
	v_lshl_add_u64 v[216:217], v[130:131], 2, s[26:27]
	v_lshl_add_u64 v[218:219], v[130:131], 1, s[12:13]
	v_bfe_u32 v130, v179, 16, 1
	v_add3_u32 v130, v179, v130, s41
	s_addk_i32 s45, 0x400
	v_add_u32_e32 v255, 0x600, v255
	v_add_u32_e32 v247, 0x600, v247
	global_store_dword v[216:217], v178, off
	global_store_short_d16_hi v[218:219], v130, off
	s_cmpk_eq_i32 s45, 0x1000
	s_cbranch_scc0 .Lp5_step
; __device__ __forceinline__ void wave_sum2(float& a, float& b) {
;     a += dpp_shr_z(a, 1); b += dpp_shr_z(b, 1); a += dpp_shr_z(a, 2); b += dpp_shr_z(b, 2); a += dpp_shr_z(a, 4); b += dpp_shr_z(b, 4); a += dpp_shr_z(a, 8); b += dpp_shr_z(b, 8);
;     a += __int_as_float(__builtin_amdgcn_update_dpp(0, __float_as_int(a), 0x142, 0xa, 0xf, false)); b += __int_as_float(__builtin_amdgcn_update_dpp(0, __float_as_int(b), 0x142, 0xa, 0xf, false));
;     a += __int_as_float(__builtin_amdgcn_update_dpp(0, __float_as_int(a), 0x143, 0xc, 0xf, false)); b += __int_as_float(__builtin_amdgcn_update_dpp(0, __float_as_int(b), 0x143, 0xc, 0xf, false));
;     a = __int_as_float(__builtin_amdgcn_readlane(__float_as_int(a), 63)); b = __int_as_float(__builtin_amdgcn_readlane(__float_as_int(b), 63));
	s_waitcnt lgkmcnt(0)
	s_andn2_b64 vcc, exec, s[66:67]
	s_cbranch_vccnz .LBB0_1077
	s_waitcnt vmcnt(26)
	v_lshlrev_b32_e32 v142, 16, v133
	s_waitcnt vmcnt(25)
	v_lshlrev_b32_e32 v146, 16, v135
	s_waitcnt vmcnt(23)
	v_lshlrev_b32_e32 v148, 16, v137
	s_waitcnt vmcnt(22)
	v_lshlrev_b32_e32 v149, 16, v150
	s_waitcnt vmcnt(21)
	v_lshlrev_b32_e32 v133, 16, v154
	s_waitcnt vmcnt(20)
	v_lshlrev_b32_e32 v143, 16, v248
	s_waitcnt vmcnt(19)
	v_lshlrev_b32_e32 v135, 16, v249
	s_waitcnt vmcnt(18)
	v_lshlrev_b32_e32 v150, 16, v250
	s_waitcnt vmcnt(17)
	v_lshlrev_b32_e32 v152, 16, v251
	s_waitcnt vmcnt(16)
	v_lshlrev_b32_e32 v137, 16, v252
	s_waitcnt vmcnt(15)
	v_lshlrev_b32_e32 v154, 16, v253
	s_waitcnt vmcnt(13)
	v_lshlrev_b32_e32 v153, 16, v220
	s_waitcnt vmcnt(12)
	v_lshlrev_b32_e32 v160, 16, v221
	s_waitcnt vmcnt(11)
	v_lshlrev_b32_e32 v162, 16, v162
	s_waitcnt vmcnt(10)
	v_lshlrev_b32_e32 v161, 16, v163
	s_waitcnt vmcnt(9)
	v_lshlrev_b32_e32 v163, 16, v222
	v_sub_f32_e32 v157, v157, v142
	v_sub_f32_e32 v130, v159, v143
	v_fma_f32 v157, v183, v157, v142
	v_add_f32_e32 v159, -1.0, v146
	v_mul_f32_e32 v158, v185, v157
	v_fma_f32 v159, v186, v159, 1.0
	v_fma_f32 v130, v182, v130, v143
	v_mul_f32_e32 v157, v159, v157
	v_mul_f32_e32 v159, v158, v158
	v_mul_f32_e32 v165, v130, v157
	v_mul_f32_e32 v166, v187, v165
	v_mov_b32_dpp v159, v159 row_shr:1 row_mask:0xf bank_mask:0xf bound_ctrl:1
	v_fmac_f32_e32 v159, v158, v158
	v_mov_b32_dpp v166, v166 row_shr:1 row_mask:0xf bank_mask:0xf bound_ctrl:1
	v_fmac_f32_e32 v166, v187, v165
	v_add_f32_dpp v159, v159, v159 row_shr:2 row_mask:0xf bank_mask:0xf bound_ctrl:1
	s_lshl_b32 s43, s43, 2
	v_add_f32_dpp v165, v166, v166 row_shr:2 row_mask:0xf bank_mask:0xf bound_ctrl:1
	v_add_f32_dpp v159, v159, v159 row_shr:4 row_mask:0xf bank_mask:0xf bound_ctrl:1
	v_mov_b32_e32 v166, v131
	v_add_f32_dpp v165, v165, v165 row_shr:4 row_mask:0xf bank_mask:0xf bound_ctrl:1
	v_add_f32_dpp v159, v159, v159 row_shr:8 row_mask:0xf bank_mask:0xf bound_ctrl:1
	s_and_b32 s43, s43, 4
	v_add_f32_dpp v165, v165, v165 row_shr:8 row_mask:0xf bank_mask:0xf bound_ctrl:1
	v_mov_b32_dpp v166, v159 row_bcast:15 row_mask:0xa bank_mask:0xf
	v_add_f32_e32 v159, v159, v166
	v_mov_b32_e32 v166, v131
	s_xor_b32 s46, s43, 4
	s_mulk_i32 s46, 0x600
	v_mov_b32_dpp v166, v165 row_bcast:15 row_mask:0xa bank_mask:0xf
	v_add_f32_e32 v165, v165, v166
	v_mov_b32_e32 v166, v131
	v_sub_f32_e32 v156, v156, v133
	v_fma_f32 v156, v184, v156, v133
	v_mov_b32_dpp v166, v159 row_bcast:31 row_mask:0xc bank_mask:0xf
	v_add_f32_e32 v159, v159, v166
	v_mov_b32_e32 v166, v131
	v_readlane_b32 s45, v159, 63
	s_nop 0
	v_mov_b32_dpp v166, v165 row_bcast:31 row_mask:0xc bank_mask:0xf
	v_max_f32_e64 v159, s45, s45
	v_max_f32_e32 v159, 0x179abe15, v159
	v_rsq_f32_e32 v159, v159
	v_add_f32_e32 v165, v165, v166
	v_mul_f32_e32 v158, v158, v159
	v_add_u32_e32 v159, s46, v180
	ds_write2st64_b32 v159, v189, v158 offset1:1
	v_mul_f32_e32 v158, v146, v158
	v_readlane_b32 s45, v165, 63
	ds_write2st64_b32 v159, v158, v157 offset0:2 offset1:3
	ds_write2st64_b32 v159, v156, v130 offset0:4 offset1:5
	v_bfe_u32 v130, v156, 16, 1
	v_mov_b32_e32 v165, v131
	v_add3_u32 v130, v156, v130, s41
	v_lshl_add_u64 v[156:157], v[164:165], 1, s[18:19]
	global_store_short_d16_hi v[156:157], v130, off
	s_and_saveexec_b64 s[66:67], s[4:5]
	s_cbranch_execz .LBB0_1070
	v_lshl_add_u32 v130, s44, 6, v140
	v_lshl_add_u64 v[156:157], v[130:131], 2, s[36:37]
	v_mov_b32_e32 v130, s45
	global_store_dword v[156:157], v130, off
